# v6 + FFN-up GEMM epilogue: row-scale loads hoisted, stores only partially drained per step (vmcnt(6) instead of vmcnt(0))
# baseline (speedup 1.0000x reference)
.LBB0_823:
	v_lshl_add_u32 v146, s6, 8, v1
	v_cndmask_b32_e64 v148, 0, 1, s[12:13]
	v_ashrrev_i32_e32 v147, 31, v146
	v_mov_b32_e32 v150, 1.0
	v_cmp_ne_u32_e64 s[6:7], 1, v148
	s_andn2_b64 vcc, exec, s[12:13]
	v_mov_b32_e32 v152, 1.0
	v_mov_b32_e32 v188, 1.0
	v_mov_b32_e32 v190, 1.0
	v_mov_b32_e32 v192, 1.0
	v_mov_b32_e32 v194, 1.0
	v_mov_b32_e32 v196, 1.0
	v_mov_b32_e32 v198, 1.0
	v_mov_b32_e32 v200, 1.0
	v_mov_b32_e32 v202, 1.0
	s_cbranch_vccnz .LBB0_825
	v_readlane_b32 s24, v247, 33
	v_readlane_b32 s25, v247, 34
	s_nop 1
	v_lshl_add_u64 v[148:149], v[146:147], 2, s[24:25]
	global_load_dword v188, v[148:149], off
	global_load_dword v190, v[148:149], off offset:64
	global_load_dword v192, v[148:149], off offset:128
	global_load_dword v194, v[148:149], off offset:192
	global_load_dword v196, v[148:149], off offset:512
	global_load_dword v198, v[148:149], off offset:576
	global_load_dword v200, v[148:149], off offset:640
	global_load_dword v202, v[148:149], off offset:704
.LBB0_825:
	v_lshl_or_b32 v148, s22, 8, v153
	v_mov_b64_e32 v[158:159], s[70:71]
	v_ashrrev_i32_e32 v149, 31, v148
	v_mad_i64_i32 v[158:159], s[24:25], v146, s43, v[158:159]
	v_lshl_add_u64 v[158:159], v[148:149], 1, v[158:159]
	s_waitcnt vmcnt(7)
	v_pk_mul_f32 v[128:129], v[128:129], v[188:189] op_sel_hi:[1,0]
	v_pk_mul_f32 v[126:127], v[126:127], v[188:189] op_sel_hi:[1,0]
	v_pk_mul_f32 v[160:161], v[124:125], v[188:189] op_sel_hi:[1,0]
	v_pk_mul_f32 v[124:125], v[122:123], v[188:189] op_sel_hi:[1,0]
	v_cvt_pk_bf16_f32 v122, v126, v127
	v_cvt_pk_bf16_f32 v123, v128, v129
	v_pk_mul_f32 v[118:119], v[118:119], v[188:189] op_sel_hi:[1,0]
	v_cvt_pk_bf16_f32 v124, v124, v125
	v_cvt_pk_bf16_f32 v125, v160, v161
	global_store_dwordx4 v[158:159], v[122:125], off
	v_pk_mul_f32 v[120:121], v[120:121], v[188:189] op_sel_hi:[1,0]
	s_and_b64 vcc, exec, s[6:7]
	v_pk_mul_f32 v[122:123], v[116:117], v[188:189] op_sel_hi:[1,0]
	v_pk_mul_f32 v[116:117], v[114:115], v[188:189] op_sel_hi:[1,0]
	v_cvt_pk_bf16_f32 v114, v118, v119
	v_cvt_pk_bf16_f32 v115, v120, v121
	s_nop 0
	v_cvt_pk_bf16_f32 v116, v116, v117
	v_cvt_pk_bf16_f32 v117, v122, v123
	global_store_dwordx4 v[158:159], v[114:117], off offset:256
	s_nop 1
	v_or_b32_e32 v114, 16, v146
	v_ashrrev_i32_e32 v115, 31, v114
	s_cbranch_vccnz .LBB0_827
	v_readlane_b32 s24, v247, 33
	v_readlane_b32 s25, v247, 34
	s_nop 1
	v_lshl_add_u64 v[116:117], v[114:115], 2, s[24:25]
.LBB0_827:
	v_mov_b64_e32 v[116:117], s[70:71]
	v_mad_i64_i32 v[114:115], s[24:25], v114, s43, v[116:117]
	v_lshl_add_u64 v[114:115], v[148:149], 1, v[114:115]
	s_waitcnt vmcnt(2)
	v_pk_mul_f32 v[112:113], v[112:113], v[190:191] op_sel_hi:[1,0]
	v_pk_mul_f32 v[110:111], v[110:111], v[190:191] op_sel_hi:[1,0]
	v_pk_mul_f32 v[116:117], v[108:109], v[190:191] op_sel_hi:[1,0]
	v_pk_mul_f32 v[108:109], v[106:107], v[190:191] op_sel_hi:[1,0]
	v_cvt_pk_bf16_f32 v106, v110, v111
	v_cvt_pk_bf16_f32 v107, v112, v113
	v_pk_mul_f32 v[102:103], v[102:103], v[190:191] op_sel_hi:[1,0]
	v_cvt_pk_bf16_f32 v108, v108, v109
	v_cvt_pk_bf16_f32 v109, v116, v117
	global_store_dwordx4 v[114:115], v[106:109], off
	v_pk_mul_f32 v[104:105], v[104:105], v[190:191] op_sel_hi:[1,0]
	s_and_b64 vcc, exec, s[6:7]
	v_pk_mul_f32 v[106:107], v[100:101], v[190:191] op_sel_hi:[1,0]
	v_pk_mul_f32 v[100:101], v[98:99], v[190:191] op_sel_hi:[1,0]
	v_cvt_pk_bf16_f32 v98, v102, v103
	v_cvt_pk_bf16_f32 v99, v104, v105
	v_or_b32_e32 v102, 32, v146
	v_cvt_pk_bf16_f32 v100, v100, v101
	v_cvt_pk_bf16_f32 v101, v106, v107
	global_store_dwordx4 v[114:115], v[98:101], off offset:256
	v_ashrrev_i32_e32 v103, 31, v102
	s_nop 0
	v_mov_b32_e32 v98, 1.0
	v_mov_b32_e32 v100, 1.0
	s_cbranch_vccnz .LBB0_829
	v_readlane_b32 s24, v247, 33
	v_readlane_b32 s25, v247, 34
	s_nop 1
	v_lshl_add_u64 v[100:101], v[102:103], 2, s[24:25]
.LBB0_829:
	v_mov_b64_e32 v[104:105], s[70:71]
	v_mad_i64_i32 v[102:103], s[24:25], v102, s43, v[104:105]
	v_lshl_add_u64 v[102:103], v[148:149], 1, v[102:103]
	s_waitcnt vmcnt(4)
	v_pk_mul_f32 v[96:97], v[96:97], v[192:193] op_sel_hi:[1,0]
	v_pk_mul_f32 v[94:95], v[94:95], v[192:193] op_sel_hi:[1,0]
	v_pk_mul_f32 v[104:105], v[92:93], v[192:193] op_sel_hi:[1,0]
	v_pk_mul_f32 v[92:93], v[90:91], v[192:193] op_sel_hi:[1,0]
	v_cvt_pk_bf16_f32 v90, v94, v95
	v_cvt_pk_bf16_f32 v91, v96, v97
	v_pk_mul_f32 v[86:87], v[86:87], v[192:193] op_sel_hi:[1,0]
	v_cvt_pk_bf16_f32 v92, v92, v93
	v_cvt_pk_bf16_f32 v93, v104, v105
	global_store_dwordx4 v[102:103], v[90:93], off
	v_pk_mul_f32 v[88:89], v[88:89], v[192:193] op_sel_hi:[1,0]
	s_and_b64 vcc, exec, s[6:7]
	v_pk_mul_f32 v[90:91], v[84:85], v[192:193] op_sel_hi:[1,0]
	v_pk_mul_f32 v[84:85], v[82:83], v[192:193] op_sel_hi:[1,0]
	v_cvt_pk_bf16_f32 v82, v86, v87
	v_cvt_pk_bf16_f32 v83, v88, v89
	s_nop 0
	v_cvt_pk_bf16_f32 v84, v84, v85
	v_cvt_pk_bf16_f32 v85, v90, v91
	global_store_dwordx4 v[102:103], v[82:85], off offset:256
	s_nop 1
	v_or_b32_e32 v82, 48, v146
	v_ashrrev_i32_e32 v83, 31, v82
	s_cbranch_vccnz .LBB0_831
	v_readlane_b32 s24, v247, 33
	v_readlane_b32 s25, v247, 34
	s_nop 1
	v_lshl_add_u64 v[84:85], v[82:83], 2, s[24:25]
.LBB0_831:
	v_mov_b64_e32 v[84:85], s[70:71]
	v_mad_i64_i32 v[82:83], s[24:25], v82, s43, v[84:85]
	v_lshl_add_u64 v[82:83], v[148:149], 1, v[82:83]
	s_waitcnt vmcnt(6)
	v_pk_mul_f32 v[80:81], v[80:81], v[194:195] op_sel_hi:[1,0]
	v_pk_mul_f32 v[78:79], v[78:79], v[194:195] op_sel_hi:[1,0]
	v_pk_mul_f32 v[84:85], v[76:77], v[194:195] op_sel_hi:[1,0]
	v_pk_mul_f32 v[76:77], v[74:75], v[194:195] op_sel_hi:[1,0]
	v_cvt_pk_bf16_f32 v74, v78, v79
	v_cvt_pk_bf16_f32 v75, v80, v81
	v_pk_mul_f32 v[70:71], v[70:71], v[194:195] op_sel_hi:[1,0]
	v_cvt_pk_bf16_f32 v76, v76, v77
	v_cvt_pk_bf16_f32 v77, v84, v85
	global_store_dwordx4 v[82:83], v[74:77], off
	v_pk_mul_f32 v[72:73], v[72:73], v[194:195] op_sel_hi:[1,0]
	s_and_b64 vcc, exec, s[6:7]
	v_pk_mul_f32 v[74:75], v[68:69], v[194:195] op_sel_hi:[1,0]
	v_pk_mul_f32 v[68:69], v[66:67], v[194:195] op_sel_hi:[1,0]
	v_cvt_pk_bf16_f32 v66, v70, v71
	v_cvt_pk_bf16_f32 v67, v72, v73
	v_add_u32_e32 v70, 0x80, v146
	v_cvt_pk_bf16_f32 v68, v68, v69
	v_cvt_pk_bf16_f32 v69, v74, v75
	global_store_dwordx4 v[82:83], v[66:69], off offset:256
	v_ashrrev_i32_e32 v71, 31, v70
	s_nop 0
	v_mov_b32_e32 v66, 1.0
	v_mov_b32_e32 v68, 1.0
	s_cbranch_vccnz .LBB0_833
	v_readlane_b32 s24, v247, 33
	v_readlane_b32 s25, v247, 34
	s_nop 1
	v_lshl_add_u64 v[68:69], v[70:71], 2, s[24:25]
.LBB0_833:
	v_mov_b64_e32 v[72:73], s[70:71]
	v_mad_i64_i32 v[70:71], s[24:25], v70, s43, v[72:73]
	v_lshl_add_u64 v[70:71], v[148:149], 1, v[70:71]
	s_waitcnt vmcnt(6)
	v_pk_mul_f32 v[64:65], v[64:65], v[196:197] op_sel_hi:[1,0]
	v_pk_mul_f32 v[62:63], v[62:63], v[196:197] op_sel_hi:[1,0]
	v_pk_mul_f32 v[72:73], v[60:61], v[196:197] op_sel_hi:[1,0]
	v_pk_mul_f32 v[60:61], v[58:59], v[196:197] op_sel_hi:[1,0]
	v_cvt_pk_bf16_f32 v58, v62, v63
	v_cvt_pk_bf16_f32 v59, v64, v65
	v_pk_mul_f32 v[54:55], v[54:55], v[196:197] op_sel_hi:[1,0]
	v_cvt_pk_bf16_f32 v60, v60, v61
	v_cvt_pk_bf16_f32 v61, v72, v73
	global_store_dwordx4 v[70:71], v[58:61], off
	v_pk_mul_f32 v[56:57], v[56:57], v[196:197] op_sel_hi:[1,0]
	s_and_b64 vcc, exec, s[6:7]
	v_pk_mul_f32 v[58:59], v[52:53], v[196:197] op_sel_hi:[1,0]
	v_pk_mul_f32 v[52:53], v[50:51], v[196:197] op_sel_hi:[1,0]
	v_cvt_pk_bf16_f32 v50, v54, v55
	v_cvt_pk_bf16_f32 v51, v56, v57
	s_nop 0
	v_cvt_pk_bf16_f32 v52, v52, v53
	v_cvt_pk_bf16_f32 v53, v58, v59
	global_store_dwordx4 v[70:71], v[50:53], off offset:256
	s_nop 1
	v_add_u32_e32 v50, 0x90, v146
	v_ashrrev_i32_e32 v51, 31, v50
	s_cbranch_vccnz .LBB0_835
	v_readlane_b32 s24, v247, 33
	v_readlane_b32 s25, v247, 34
	s_nop 1
	v_lshl_add_u64 v[52:53], v[50:51], 2, s[24:25]
.LBB0_835:
	v_mov_b64_e32 v[52:53], s[70:71]
	v_mad_i64_i32 v[50:51], s[24:25], v50, s43, v[52:53]
	v_lshl_add_u64 v[50:51], v[148:149], 1, v[50:51]
	s_waitcnt vmcnt(6)
	v_pk_mul_f32 v[48:49], v[48:49], v[198:199] op_sel_hi:[1,0]
	v_pk_mul_f32 v[46:47], v[46:47], v[198:199] op_sel_hi:[1,0]
	v_pk_mul_f32 v[52:53], v[44:45], v[198:199] op_sel_hi:[1,0]
	v_pk_mul_f32 v[44:45], v[42:43], v[198:199] op_sel_hi:[1,0]
	v_cvt_pk_bf16_f32 v42, v46, v47
	v_cvt_pk_bf16_f32 v43, v48, v49
	v_pk_mul_f32 v[38:39], v[38:39], v[198:199] op_sel_hi:[1,0]
	v_cvt_pk_bf16_f32 v44, v44, v45
	v_cvt_pk_bf16_f32 v45, v52, v53
	global_store_dwordx4 v[50:51], v[42:45], off
	v_pk_mul_f32 v[40:41], v[40:41], v[198:199] op_sel_hi:[1,0]
	s_and_b64 vcc, exec, s[6:7]
	v_pk_mul_f32 v[42:43], v[36:37], v[198:199] op_sel_hi:[1,0]
	v_pk_mul_f32 v[36:37], v[34:35], v[198:199] op_sel_hi:[1,0]
	v_cvt_pk_bf16_f32 v34, v38, v39
	v_cvt_pk_bf16_f32 v35, v40, v41
	v_add_u32_e32 v38, 0xa0, v146
	v_cvt_pk_bf16_f32 v36, v36, v37
	v_cvt_pk_bf16_f32 v37, v42, v43
	global_store_dwordx4 v[50:51], v[34:37], off offset:256
	v_ashrrev_i32_e32 v39, 31, v38
	s_nop 0
	v_mov_b32_e32 v34, 1.0
	v_mov_b32_e32 v36, 1.0
	s_cbranch_vccnz .LBB0_837
	v_readlane_b32 s24, v247, 33
	v_readlane_b32 s25, v247, 34
	s_nop 1
	v_lshl_add_u64 v[36:37], v[38:39], 2, s[24:25]
.LBB0_837:
	v_mov_b64_e32 v[40:41], s[70:71]
	v_mad_i64_i32 v[38:39], s[24:25], v38, s43, v[40:41]
	v_lshl_add_u64 v[38:39], v[148:149], 1, v[38:39]
	s_waitcnt vmcnt(6)
	v_pk_mul_f32 v[32:33], v[32:33], v[200:201] op_sel_hi:[1,0]
	v_pk_mul_f32 v[30:31], v[30:31], v[200:201] op_sel_hi:[1,0]
	v_pk_mul_f32 v[40:41], v[28:29], v[200:201] op_sel_hi:[1,0]
	v_pk_mul_f32 v[28:29], v[26:27], v[200:201] op_sel_hi:[1,0]
	v_cvt_pk_bf16_f32 v26, v30, v31
	v_cvt_pk_bf16_f32 v27, v32, v33
	v_pk_mul_f32 v[22:23], v[22:23], v[200:201] op_sel_hi:[1,0]
	v_cvt_pk_bf16_f32 v28, v28, v29
	v_cvt_pk_bf16_f32 v29, v40, v41
	global_store_dwordx4 v[38:39], v[26:29], off
	v_pk_mul_f32 v[24:25], v[24:25], v[200:201] op_sel_hi:[1,0]
	s_and_b64 vcc, exec, s[6:7]
	v_pk_mul_f32 v[26:27], v[20:21], v[200:201] op_sel_hi:[1,0]
	v_pk_mul_f32 v[20:21], v[18:19], v[200:201] op_sel_hi:[1,0]
	v_cvt_pk_bf16_f32 v18, v22, v23
	v_cvt_pk_bf16_f32 v19, v24, v25
	s_nop 0
	v_cvt_pk_bf16_f32 v20, v20, v21
	v_cvt_pk_bf16_f32 v21, v26, v27
	global_store_dwordx4 v[38:39], v[18:21], off offset:256
	s_nop 1
	v_add_u32_e32 v18, 0xb0, v146
	v_ashrrev_i32_e32 v19, 31, v18
	s_cbranch_vccnz .LBB0_839
	v_readlane_b32 s6, v247, 33
	v_readlane_b32 s7, v247, 34
	s_nop 1
	v_lshl_add_u64 v[20:21], v[18:19], 2, s[6:7]
.LBB0_839:
	v_mov_b64_e32 v[20:21], s[70:71]
	v_mad_i64_i32 v[18:19], s[6:7], v18, s43, v[20:21]
	v_lshl_add_u64 v[18:19], v[148:149], 1, v[18:19]
	s_waitcnt vmcnt(6)
	v_pk_mul_f32 v[16:17], v[16:17], v[202:203] op_sel_hi:[1,0]
	v_pk_mul_f32 v[14:15], v[14:15], v[202:203] op_sel_hi:[1,0]
	v_pk_mul_f32 v[20:21], v[12:13], v[202:203] op_sel_hi:[1,0]
	v_pk_mul_f32 v[12:13], v[10:11], v[202:203] op_sel_hi:[1,0]
	v_cvt_pk_bf16_f32 v10, v14, v15
	v_cvt_pk_bf16_f32 v11, v16, v17
	s_andn2_b64 vcc, exec, s[4:5]
	v_cvt_pk_bf16_f32 v12, v12, v13
	v_cvt_pk_bf16_f32 v13, v20, v21
	global_store_dwordx4 v[18:19], v[10:13], off
	s_mov_b64 s[4:5], -1
	v_pk_mul_f32 v[8:9], v[8:9], v[202:203] op_sel_hi:[1,0]
	v_pk_mul_f32 v[10:11], v[4:5], v[202:203] op_sel_hi:[1,0]
	v_pk_mul_f32 v[4:5], v[2:3], v[202:203] op_sel_hi:[1,0]
	v_pk_mul_f32 v[6:7], v[6:7], v[202:203] op_sel_hi:[1,0]
	s_nop 0
	v_cvt_pk_bf16_f32 v2, v6, v7
	v_cvt_pk_bf16_f32 v3, v8, v9
	v_cvt_pk_bf16_f32 v4, v4, v5
	v_cvt_pk_bf16_f32 v5, v10, v11
	global_store_dwordx4 v[18:19], v[2:5], off offset:256
	s_cbranch_vccnz .LBB0_816
	s_andn2_b64 vcc, exec, s[2:3]
	s_cbranch_vccnz .LBB0_815
	s_barrier
	s_branch .LBB0_815

.LBB0_1700:
	v_lshl_or_b32 v148, s22, 8, v153
	v_mov_b64_e32 v[158:159], s[70:71]
	v_ashrrev_i32_e32 v149, 31, v148
	v_mad_i64_i32 v[158:159], s[24:25], v146, s45, v[158:159]
	v_lshl_add_u64 v[158:159], v[148:149], 1, v[158:159]
	s_waitcnt vmcnt(7)
	v_pk_mul_f32 v[128:129], v[128:129], v[188:189] op_sel_hi:[1,0]
	v_pk_mul_f32 v[126:127], v[126:127], v[188:189] op_sel_hi:[1,0]
	v_pk_mul_f32 v[160:161], v[124:125], v[188:189] op_sel_hi:[1,0]
	v_pk_mul_f32 v[124:125], v[122:123], v[188:189] op_sel_hi:[1,0]
	v_cvt_pk_bf16_f32 v122, v126, v127
	v_cvt_pk_bf16_f32 v123, v128, v129
	v_pk_mul_f32 v[118:119], v[118:119], v[188:189] op_sel_hi:[1,0]
	v_cvt_pk_bf16_f32 v124, v124, v125
	v_cvt_pk_bf16_f32 v125, v160, v161
	global_store_dwordx4 v[158:159], v[122:125], off
	v_pk_mul_f32 v[120:121], v[120:121], v[188:189] op_sel_hi:[1,0]
	s_and_b64 vcc, exec, s[6:7]
	v_pk_mul_f32 v[122:123], v[116:117], v[188:189] op_sel_hi:[1,0]
	v_pk_mul_f32 v[116:117], v[114:115], v[188:189] op_sel_hi:[1,0]
	v_cvt_pk_bf16_f32 v114, v118, v119
	v_cvt_pk_bf16_f32 v115, v120, v121
	s_nop 0
	v_cvt_pk_bf16_f32 v116, v116, v117
	v_cvt_pk_bf16_f32 v117, v122, v123
	global_store_dwordx4 v[158:159], v[114:117], off offset:256
	s_nop 1
	v_or_b32_e32 v114, 16, v146
	v_ashrrev_i32_e32 v115, 31, v114
	s_cbranch_vccnz .LBB0_1702
	v_readlane_b32 s24, v247, 33
	v_readlane_b32 s25, v247, 34
	s_nop 1
	v_lshl_add_u64 v[116:117], v[114:115], 2, s[24:25]
.LBB0_1702:
	v_mov_b64_e32 v[116:117], s[70:71]
	v_mad_i64_i32 v[114:115], s[24:25], v114, s45, v[116:117]
	v_lshl_add_u64 v[114:115], v[148:149], 1, v[114:115]
	s_waitcnt vmcnt(2)
	v_pk_mul_f32 v[112:113], v[112:113], v[190:191] op_sel_hi:[1,0]
	v_pk_mul_f32 v[110:111], v[110:111], v[190:191] op_sel_hi:[1,0]
	v_pk_mul_f32 v[116:117], v[108:109], v[190:191] op_sel_hi:[1,0]
	v_pk_mul_f32 v[108:109], v[106:107], v[190:191] op_sel_hi:[1,0]
	v_cvt_pk_bf16_f32 v106, v110, v111
	v_cvt_pk_bf16_f32 v107, v112, v113
	v_pk_mul_f32 v[102:103], v[102:103], v[190:191] op_sel_hi:[1,0]
	v_cvt_pk_bf16_f32 v108, v108, v109
	v_cvt_pk_bf16_f32 v109, v116, v117
	global_store_dwordx4 v[114:115], v[106:109], off
	v_pk_mul_f32 v[104:105], v[104:105], v[190:191] op_sel_hi:[1,0]
	s_and_b64 vcc, exec, s[6:7]
	v_pk_mul_f32 v[106:107], v[100:101], v[190:191] op_sel_hi:[1,0]
	v_pk_mul_f32 v[100:101], v[98:99], v[190:191] op_sel_hi:[1,0]
	v_cvt_pk_bf16_f32 v98, v102, v103
	v_cvt_pk_bf16_f32 v99, v104, v105
	v_or_b32_e32 v102, 32, v146
	v_cvt_pk_bf16_f32 v100, v100, v101
	v_cvt_pk_bf16_f32 v101, v106, v107
	global_store_dwordx4 v[114:115], v[98:101], off offset:256
	v_ashrrev_i32_e32 v103, 31, v102
	s_nop 0
	v_mov_b32_e32 v98, 1.0
	v_mov_b32_e32 v100, 1.0
	s_cbranch_vccnz .LBB0_1704
	v_readlane_b32 s24, v247, 33
	v_readlane_b32 s25, v247, 34
	s_nop 1
	v_lshl_add_u64 v[100:101], v[102:103], 2, s[24:25]
.LBB0_1704:
	v_mov_b64_e32 v[104:105], s[70:71]
	v_mad_i64_i32 v[102:103], s[24:25], v102, s45, v[104:105]
	v_lshl_add_u64 v[102:103], v[148:149], 1, v[102:103]
	s_waitcnt vmcnt(4)
	v_pk_mul_f32 v[96:97], v[96:97], v[192:193] op_sel_hi:[1,0]
	v_pk_mul_f32 v[94:95], v[94:95], v[192:193] op_sel_hi:[1,0]
	v_pk_mul_f32 v[104:105], v[92:93], v[192:193] op_sel_hi:[1,0]
	v_pk_mul_f32 v[92:93], v[90:91], v[192:193] op_sel_hi:[1,0]
	v_cvt_pk_bf16_f32 v90, v94, v95
	v_cvt_pk_bf16_f32 v91, v96, v97
	v_pk_mul_f32 v[86:87], v[86:87], v[192:193] op_sel_hi:[1,0]
	v_cvt_pk_bf16_f32 v92, v92, v93
	v_cvt_pk_bf16_f32 v93, v104, v105
	global_store_dwordx4 v[102:103], v[90:93], off
	v_pk_mul_f32 v[88:89], v[88:89], v[192:193] op_sel_hi:[1,0]
	s_and_b64 vcc, exec, s[6:7]
	v_pk_mul_f32 v[90:91], v[84:85], v[192:193] op_sel_hi:[1,0]
	v_pk_mul_f32 v[84:85], v[82:83], v[192:193] op_sel_hi:[1,0]
	v_cvt_pk_bf16_f32 v82, v86, v87
	v_cvt_pk_bf16_f32 v83, v88, v89
	s_nop 0
	v_cvt_pk_bf16_f32 v84, v84, v85
	v_cvt_pk_bf16_f32 v85, v90, v91
	global_store_dwordx4 v[102:103], v[82:85], off offset:256
	s_nop 1
	v_or_b32_e32 v82, 48, v146
	v_ashrrev_i32_e32 v83, 31, v82
	s_cbranch_vccnz .LBB0_1706
	v_readlane_b32 s24, v247, 33
	v_readlane_b32 s25, v247, 34
	s_nop 1
	v_lshl_add_u64 v[84:85], v[82:83], 2, s[24:25]
.LBB0_1706:
	v_mov_b64_e32 v[84:85], s[70:71]
	v_mad_i64_i32 v[82:83], s[24:25], v82, s45, v[84:85]
	v_lshl_add_u64 v[82:83], v[148:149], 1, v[82:83]
	s_waitcnt vmcnt(6)
	v_pk_mul_f32 v[80:81], v[80:81], v[194:195] op_sel_hi:[1,0]
	v_pk_mul_f32 v[78:79], v[78:79], v[194:195] op_sel_hi:[1,0]
	v_pk_mul_f32 v[84:85], v[76:77], v[194:195] op_sel_hi:[1,0]
	v_pk_mul_f32 v[76:77], v[74:75], v[194:195] op_sel_hi:[1,0]
	v_cvt_pk_bf16_f32 v74, v78, v79
	v_cvt_pk_bf16_f32 v75, v80, v81
	v_pk_mul_f32 v[70:71], v[70:71], v[194:195] op_sel_hi:[1,0]
	v_cvt_pk_bf16_f32 v76, v76, v77
	v_cvt_pk_bf16_f32 v77, v84, v85
	global_store_dwordx4 v[82:83], v[74:77], off
	v_pk_mul_f32 v[72:73], v[72:73], v[194:195] op_sel_hi:[1,0]
	s_and_b64 vcc, exec, s[6:7]
	v_pk_mul_f32 v[74:75], v[68:69], v[194:195] op_sel_hi:[1,0]
	v_pk_mul_f32 v[68:69], v[66:67], v[194:195] op_sel_hi:[1,0]
	v_cvt_pk_bf16_f32 v66, v70, v71
	v_cvt_pk_bf16_f32 v67, v72, v73
	v_add_u32_e32 v70, 0x80, v146
	v_cvt_pk_bf16_f32 v68, v68, v69
	v_cvt_pk_bf16_f32 v69, v74, v75
	global_store_dwordx4 v[82:83], v[66:69], off offset:256
	v_ashrrev_i32_e32 v71, 31, v70
	s_nop 0
	v_mov_b32_e32 v66, 1.0
	v_mov_b32_e32 v68, 1.0
	s_cbranch_vccnz .LBB0_1708
	v_readlane_b32 s24, v247, 33
	v_readlane_b32 s25, v247, 34
	s_nop 1
	v_lshl_add_u64 v[68:69], v[70:71], 2, s[24:25]
.LBB0_1708:
	v_mov_b64_e32 v[72:73], s[70:71]
	v_mad_i64_i32 v[70:71], s[24:25], v70, s45, v[72:73]
	v_lshl_add_u64 v[70:71], v[148:149], 1, v[70:71]
	s_waitcnt vmcnt(6)
	v_pk_mul_f32 v[64:65], v[64:65], v[196:197] op_sel_hi:[1,0]
	v_pk_mul_f32 v[62:63], v[62:63], v[196:197] op_sel_hi:[1,0]
	v_pk_mul_f32 v[72:73], v[60:61], v[196:197] op_sel_hi:[1,0]
	v_pk_mul_f32 v[60:61], v[58:59], v[196:197] op_sel_hi:[1,0]
	v_cvt_pk_bf16_f32 v58, v62, v63
	v_cvt_pk_bf16_f32 v59, v64, v65
	v_pk_mul_f32 v[54:55], v[54:55], v[196:197] op_sel_hi:[1,0]
	v_cvt_pk_bf16_f32 v60, v60, v61
	v_cvt_pk_bf16_f32 v61, v72, v73
	global_store_dwordx4 v[70:71], v[58:61], off
	v_pk_mul_f32 v[56:57], v[56:57], v[196:197] op_sel_hi:[1,0]
	s_and_b64 vcc, exec, s[6:7]
	v_pk_mul_f32 v[58:59], v[52:53], v[196:197] op_sel_hi:[1,0]
	v_pk_mul_f32 v[52:53], v[50:51], v[196:197] op_sel_hi:[1,0]
	v_cvt_pk_bf16_f32 v50, v54, v55
	v_cvt_pk_bf16_f32 v51, v56, v57
	s_nop 0
	v_cvt_pk_bf16_f32 v52, v52, v53
	v_cvt_pk_bf16_f32 v53, v58, v59
	global_store_dwordx4 v[70:71], v[50:53], off offset:256
	s_nop 1
	v_add_u32_e32 v50, 0x90, v146
	v_ashrrev_i32_e32 v51, 31, v50
	s_cbranch_vccnz .LBB0_1710
	v_readlane_b32 s24, v247, 33
	v_readlane_b32 s25, v247, 34
	s_nop 1
	v_lshl_add_u64 v[52:53], v[50:51], 2, s[24:25]
.LBB0_1710:
	v_mov_b64_e32 v[52:53], s[70:71]
	v_mad_i64_i32 v[50:51], s[24:25], v50, s45, v[52:53]
	v_lshl_add_u64 v[50:51], v[148:149], 1, v[50:51]
	s_waitcnt vmcnt(6)
	v_pk_mul_f32 v[48:49], v[48:49], v[198:199] op_sel_hi:[1,0]
	v_pk_mul_f32 v[46:47], v[46:47], v[198:199] op_sel_hi:[1,0]
	v_pk_mul_f32 v[52:53], v[44:45], v[198:199] op_sel_hi:[1,0]
	v_pk_mul_f32 v[44:45], v[42:43], v[198:199] op_sel_hi:[1,0]
	v_cvt_pk_bf16_f32 v42, v46, v47
	v_cvt_pk_bf16_f32 v43, v48, v49
	v_pk_mul_f32 v[38:39], v[38:39], v[198:199] op_sel_hi:[1,0]
	v_cvt_pk_bf16_f32 v44, v44, v45
	v_cvt_pk_bf16_f32 v45, v52, v53
	global_store_dwordx4 v[50:51], v[42:45], off
	v_pk_mul_f32 v[40:41], v[40:41], v[198:199] op_sel_hi:[1,0]
	s_and_b64 vcc, exec, s[6:7]
	v_pk_mul_f32 v[42:43], v[36:37], v[198:199] op_sel_hi:[1,0]
	v_pk_mul_f32 v[36:37], v[34:35], v[198:199] op_sel_hi:[1,0]
	v_cvt_pk_bf16_f32 v34, v38, v39
	v_cvt_pk_bf16_f32 v35, v40, v41
	v_add_u32_e32 v38, 0xa0, v146
	v_cvt_pk_bf16_f32 v36, v36, v37
	v_cvt_pk_bf16_f32 v37, v42, v43
	global_store_dwordx4 v[50:51], v[34:37], off offset:256
	v_ashrrev_i32_e32 v39, 31, v38
	s_nop 0
	v_mov_b32_e32 v34, 1.0
	v_mov_b32_e32 v36, 1.0
	s_cbranch_vccnz .LBB0_1712
	v_readlane_b32 s24, v247, 33
	v_readlane_b32 s25, v247, 34
	s_nop 1
	v_lshl_add_u64 v[36:37], v[38:39], 2, s[24:25]
.LBB0_1712:
	v_mov_b64_e32 v[40:41], s[70:71]
	v_mad_i64_i32 v[38:39], s[24:25], v38, s45, v[40:41]
	v_lshl_add_u64 v[38:39], v[148:149], 1, v[38:39]
	s_waitcnt vmcnt(6)
	v_pk_mul_f32 v[32:33], v[32:33], v[200:201] op_sel_hi:[1,0]
	v_pk_mul_f32 v[30:31], v[30:31], v[200:201] op_sel_hi:[1,0]
	v_pk_mul_f32 v[40:41], v[28:29], v[200:201] op_sel_hi:[1,0]
	v_pk_mul_f32 v[28:29], v[26:27], v[200:201] op_sel_hi:[1,0]
	v_cvt_pk_bf16_f32 v26, v30, v31
	v_cvt_pk_bf16_f32 v27, v32, v33
	v_pk_mul_f32 v[22:23], v[22:23], v[200:201] op_sel_hi:[1,0]
	v_cvt_pk_bf16_f32 v28, v28, v29
	v_cvt_pk_bf16_f32 v29, v40, v41
	global_store_dwordx4 v[38:39], v[26:29], off
	v_pk_mul_f32 v[24:25], v[24:25], v[200:201] op_sel_hi:[1,0]
	s_and_b64 vcc, exec, s[6:7]
	v_pk_mul_f32 v[26:27], v[20:21], v[200:201] op_sel_hi:[1,0]
	v_pk_mul_f32 v[20:21], v[18:19], v[200:201] op_sel_hi:[1,0]
	v_cvt_pk_bf16_f32 v18, v22, v23
	v_cvt_pk_bf16_f32 v19, v24, v25
	s_nop 0
	v_cvt_pk_bf16_f32 v20, v20, v21
	v_cvt_pk_bf16_f32 v21, v26, v27
	global_store_dwordx4 v[38:39], v[18:21], off offset:256
	s_nop 1
	v_add_u32_e32 v18, 0xb0, v146
	v_ashrrev_i32_e32 v19, 31, v18
	s_cbranch_vccnz .LBB0_1714
	v_readlane_b32 s6, v247, 33
	v_readlane_b32 s7, v247, 34
	s_nop 1
	v_lshl_add_u64 v[20:21], v[18:19], 2, s[6:7]
.LBB0_1714:
	v_mov_b64_e32 v[20:21], s[70:71]
	v_mad_i64_i32 v[18:19], s[6:7], v18, s45, v[20:21]
	v_lshl_add_u64 v[18:19], v[148:149], 1, v[18:19]
	s_waitcnt vmcnt(6)
	v_pk_mul_f32 v[16:17], v[16:17], v[202:203] op_sel_hi:[1,0]
	v_pk_mul_f32 v[14:15], v[14:15], v[202:203] op_sel_hi:[1,0]
	v_pk_mul_f32 v[20:21], v[12:13], v[202:203] op_sel_hi:[1,0]
	v_pk_mul_f32 v[12:13], v[10:11], v[202:203] op_sel_hi:[1,0]
	v_cvt_pk_bf16_f32 v10, v14, v15
	v_cvt_pk_bf16_f32 v11, v16, v17
	s_andn2_b64 vcc, exec, s[4:5]
	v_cvt_pk_bf16_f32 v12, v12, v13
	v_cvt_pk_bf16_f32 v13, v20, v21
	global_store_dwordx4 v[18:19], v[10:13], off
	s_mov_b64 s[4:5], -1
	v_pk_mul_f32 v[8:9], v[8:9], v[202:203] op_sel_hi:[1,0]
	v_pk_mul_f32 v[10:11], v[4:5], v[202:203] op_sel_hi:[1,0]
	v_pk_mul_f32 v[4:5], v[2:3], v[202:203] op_sel_hi:[1,0]
	v_pk_mul_f32 v[6:7], v[6:7], v[202:203] op_sel_hi:[1,0]
	s_nop 0
	v_cvt_pk_bf16_f32 v2, v6, v7
	v_cvt_pk_bf16_f32 v3, v8, v9
	v_cvt_pk_bf16_f32 v4, v4, v5
	v_cvt_pk_bf16_f32 v5, v10, v11
	global_store_dwordx4 v[18:19], v[2:5], off offset:256
	s_cbranch_vccnz .LBB0_1691
	s_andn2_b64 vcc, exec, s[2:3]
	s_cbranch_vccnz .LBB0_1690
	s_barrier
	s_branch .LBB0_1690
